# attention: static s_setprio 1 for waves 4-7 during the attention phase; rescale branch reuses the threshold compare (no v_cmp_neq on exp result)
# baseline (speedup 1.0000x reference)
; #define LAUNDER() int tid, blk = blk0, G = G0; asm volatile("v_mbcnt_lo_u32_b32 %0, -1, 0\n\tv_mbcnt_hi_u32_b32 %0, -1, %0" : "=v"(tid)); tid += wave_s * 64; asm volatile("" : "+v"(tid), "+s"(blk), "+s"(G))
; #define GRID_BAR() do { xcd_barrier(xbar); } while (0)
; __device__ __forceinline__ void attn_phase(unsigned char* lds, const Params& p, int jl, const bf16_t* proj, bf16_t* mix, int blk, int G, int tid) {
;     ...
;     for (int gi = blk * 512 + tid; gi < 2560 * 2 * 256; gi += G * 512) {
;         const int c8 = gi & 255, kv = (gi >> 8) & 1, r = gi >> 9;
;         size_t srow, dst;
;         if (r < 2048) { const int b = r >> 9, tp = r & 511; srow = (size_t)b * 8192 + 7680 + tp; dst = (kv ? O_CVP : O_CKP) + ((size_t)(jl * 4 + b) * 512 + tp) * DM + c8 * 8; }
;         else { const int rs = r - 2048; srow = (size_t)MPR + rs; dst = (kv ? O_CVS : O_CKS) + ((size_t)jl * 512 + rs) * DM + c8 * 8; }
;         const bf16x8 x = *(const bf16x8*)(proj + srow * N4 + 2048 + kv * 2048 + c8 * 8);
; __global__ void __launch_bounds__(512, 2) fwd_kernel(Params p) {
;     ...
;         if ((layer & 1) == 0) { { LAUNDER(); hgrn_a(lds, p, jl, proj, mix, dbuf, scr, useg, dseg, blk, G, tid); } GRID_BAR(); { LAUNDER(); hgrn_b(lds, p, jl, proj, mix, dbuf, scr, useg, dseg, blk, G, tid); } }
;         else { LAUNDER(); attn_phase(lds, p, jl, proj, mix, blk, G, tid); }
.LBB0_122:
	s_or_b64 exec, exec, s[2:3]
	v_readlane_b32 s2, v255, 24
	v_readlane_b32 s3, v255, 25
	s_lshr_b32 s3, s2, 1
	s_bitcmp1_b32 s2, 0
	s_cselect_b64 s[4:5], -1, 0
	v_writelane_b32 v255, s3, 26
	s_mov_b64 s[2:3], -1
	s_and_b64 vcc, exec, s[4:5]
	s_waitcnt lgkmcnt(0)
	s_barrier
	s_cbranch_vccz .LBB0_223
	s_cmp_lt_u32 s62, 0x100
	s_cbranch_scc1 .Lattn_prio_skip
	s_setprio 1
.Lattn_prio_skip:
	v_mbcnt_lo_u32_b32 v0, -1, 0
	v_mbcnt_hi_u32_b32 v0, -1, v0
	s_mov_b32 s22, s64
	v_add_u32_e32 v158, s62, v0
	s_mov_b32 s23, s65
	s_mov_b32 s2, 0x140000
	v_lshl_add_u32 v3, s22, 9, v158
	v_cmp_gt_i32_e32 vcc, s2, v3
	s_and_saveexec_b64 s[2:3], vcc
	s_cbranch_execz .LBB0_130
	v_lshlrev_b32_e32 v0, 3, v158
	v_readlane_b32 s4, v255, 26
	v_and_b32_e32 v2, 0x7f8, v0
	s_lshl_b32 s8, s4, 2
	s_lshl_b32 s9, s23, 9
	v_lshl_or_b32 v4, s4, 20, v2
	v_mov_b32_e32 v5, v1
	s_mov_b64 s[4:5], 0
	s_branch .LBB0_126

; __device__ __forceinline__ void attn_phase(unsigned char* lds, const Params& p, int jl, const bf16_t* proj, bf16_t* mix, int blk, int G, int tid) {
;     ...
;             if (t >= w_lo && t <= w_hi) {
;                 const bf16_t* ks = KS + buf * (64 * 136); const bf16_t* vt = VT + buf * (128 * 72);
;                 const int nvk = (samp && t == 8) ? 32 : 64;
;                 f32x4 s[2][4];
; #pragma unroll
;                 for (int qt = 0; qt < 2; ++qt)
; #pragma unroll
;                     for (int kt = 0; kt < 4; ++kt) s[qt][kt] = (f32x4){0.f, 0.f, 0.f, 0.f};
; #pragma unroll
;                 for (int kh2 = 0; kh2 < 2; ++kh2) { bf16x8 kf[2][4];
; #pragma unroll
;                     for (int kt = 0; kt < 2; ++kt)
; #pragma unroll
;                         for (int k4 = 0; k4 < 4; ++k4) kf[kt][k4] = *(const bf16x8*)(ks + ((kh2 * 2 + kt) * 16 + fr) * 136 + k4 * 32 + fq * 8);
;                     __builtin_amdgcn_sched_barrier(0);
; #pragma unroll
;                     for (int k4 = 0; k4 < 4; ++k4)
; #pragma unroll
;                         for (int kt = 0; kt < 2; ++kt)
; #pragma unroll
;                             for (int qt = 0; qt < 2; ++qt) s[qt][kh2 * 2 + kt] = MFMA16(kf[kt][k4], qf[qt][k4], s[qt][kh2 * 2 + kt]);
;                     __builtin_amdgcn_sched_barrier(0); }
;                 bf16x8 vf[4][2][2];
;     ...
;                 ATT_VLOAD(0);
;                 __builtin_amdgcn_sched_barrier(0);
;                 bf16x8 pb[2][2];
; #pragma unroll
;                 for (int qt = 0; qt < 2; ++qt) {
;                     const float* bp = BIAS + (575 - (qpos0 + qt * 16 - t * 64 - fq * 4));
; #pragma unroll
;                     for (int kt = 0; kt < 4; ++kt) { const f32x4 bv = {bp[kt * 16], bp[kt * 16 + 1], bp[kt * 16 + 2], bp[kt * 16 + 3]}; s[qt][kt] = s[qt][kt] * SC2 + bv; }
;                     if (nvk < 64) {
; #pragma unroll
;                         for (int kt = 0; kt < 4; ++kt)
; #pragma unroll
;                             for (int j = 0; j < 4; ++j) if (kt * 16 + fq * 4 + j >= nvk) s[qt][kt][j] = NEG_INF; }
;                     float mx;
;                     { const f32x4 m01 = __builtin_elementwise_max(s[qt][0], s[qt][1]), m23 = __builtin_elementwise_max(s[qt][2], s[qt][3]), m4 = __builtin_elementwise_max(m01, m23);
;                       mx = fmaxf(fmaxf(m4[0], m4[1]), fmaxf(m4[2], m4[3])); }
.LBB0_205:
	v_cmp_ge_i32_e32 vcc, s47, v202
	v_cmp_le_i32_e64 s[4:5], s47, v203
	s_and_b32 s20, s35, 1
	s_and_b64 s[4:5], vcc, s[4:5]
	s_and_saveexec_b64 s[18:19], s[4:5]
	s_cbranch_execz .LBB0_211
	s_mul_i32 s4, s20, 0x4400
	v_add_u32_e32 v0, s4, v195
	ds_read_b128 v[116:119], v0
	ds_read_b128 v[120:123], v0 offset:64
	ds_read_b128 v[124:127], v0 offset:128
	ds_read_b128 v[128:131], v0 offset:192
	ds_read_b128 v[132:135], v0 offset:4352
	ds_read_b128 v[136:139], v0 offset:4416
	ds_read_b128 v[140:143], v0 offset:4480
	ds_read_b128 v[144:147], v0 offset:4544
	s_cmp_eq_u32 s47, 8
	s_mul_i32 s21, s20, 0x4800
	s_cselect_b64 s[4:5], -1, 0
	s_and_b64 s[4:5], s[6:7], s[4:5]
	s_add_i32 s21, s21, 0
	s_waitcnt lgkmcnt(7)
	v_mfma_f32_16x16x32_bf16 v[168:171], v[116:119], v[52:55], 0
	v_mfma_f32_16x16x32_bf16 v[116:119], v[116:119], v[76:79], 0
	s_waitcnt lgkmcnt(3)
	v_mfma_f32_16x16x32_bf16 v[172:175], v[132:135], v[52:55], 0
	v_mfma_f32_16x16x32_bf16 v[132:135], v[132:135], v[76:79], 0
	v_mfma_f32_16x16x32_bf16 v[168:171], v[120:123], v[56:59], v[168:171]
	v_mfma_f32_16x16x32_bf16 v[116:119], v[120:123], v[68:71], v[116:119]
	s_waitcnt lgkmcnt(2)
	v_mfma_f32_16x16x32_bf16 v[120:123], v[136:139], v[56:59], v[172:175]
	v_mfma_f32_16x16x32_bf16 v[132:135], v[136:139], v[68:71], v[132:135]
	v_mfma_f32_16x16x32_bf16 v[136:139], v[124:127], v[60:63], v[168:171]
	v_mfma_f32_16x16x32_bf16 v[116:119], v[124:127], v[72:75], v[116:119]
	s_waitcnt lgkmcnt(1)
	v_mfma_f32_16x16x32_bf16 v[120:123], v[140:143], v[60:63], v[120:123]
	v_mfma_f32_16x16x32_bf16 v[124:127], v[140:143], v[72:75], v[132:135]
	v_mfma_f32_16x16x32_bf16 v[170:173], v[128:131], v[64:67], v[136:139]
	v_mfma_f32_16x16x32_bf16 v[132:135], v[128:131], v[80:83], v[116:119]
	s_waitcnt lgkmcnt(0)
	v_mfma_f32_16x16x32_bf16 v[182:185], v[144:147], v[64:67], v[120:123]
	v_mfma_f32_16x16x32_bf16 v[136:139], v[144:147], v[80:83], v[124:127]
	ds_read_b128 v[116:119], v0 offset:8704
	s_nop 0
	ds_read_b128 v[120:123], v0 offset:8768
	ds_read_b128 v[124:127], v0 offset:8832
	ds_read_b128 v[128:131], v0 offset:8896
	ds_read_b128 v[140:143], v0 offset:13056
	ds_read_b128 v[144:147], v0 offset:13120
	ds_read_b128 v[174:177], v0 offset:13184
	ds_read_b128 v[178:181], v0 offset:13248
	s_waitcnt lgkmcnt(7)
	v_mfma_f32_16x16x32_bf16 v[216:219], v[116:119], v[52:55], 0
	v_mfma_f32_16x16x32_bf16 v[116:119], v[116:119], v[76:79], 0
	s_waitcnt lgkmcnt(3)
	v_mfma_f32_16x16x32_bf16 v[220:223], v[140:143], v[52:55], 0
	v_mfma_f32_16x16x32_bf16 v[140:143], v[140:143], v[76:79], 0
	v_mfma_f32_16x16x32_bf16 v[216:219], v[120:123], v[56:59], v[216:219]
	v_mfma_f32_16x16x32_bf16 v[116:119], v[120:123], v[68:71], v[116:119]
	s_waitcnt lgkmcnt(2)
	v_mfma_f32_16x16x32_bf16 v[140:143], v[144:147], v[68:71], v[140:143]
	v_mfma_f32_16x16x32_bf16 v[120:123], v[144:147], v[56:59], v[220:223]
	v_mfma_f32_16x16x32_bf16 v[144:147], v[124:127], v[60:63], v[216:219]
	v_mfma_f32_16x16x32_bf16 v[116:119], v[124:127], v[72:75], v[116:119]
	s_waitcnt lgkmcnt(1)
	v_mfma_f32_16x16x32_bf16 v[124:127], v[174:177], v[72:75], v[140:143]
	v_mfma_f32_16x16x32_bf16 v[120:123], v[174:177], v[60:63], v[120:123]
	v_mfma_f32_16x16x32_bf16 v[222:225], v[128:131], v[64:67], v[144:147]
	v_mfma_f32_16x16x32_bf16 v[144:147], v[128:131], v[80:83], v[116:119]
	s_waitcnt lgkmcnt(0)
	v_mfma_f32_16x16x32_bf16 v[140:143], v[178:181], v[80:83], v[124:127]
	v_mfma_f32_16x16x32_bf16 v[226:229], v[178:181], v[64:67], v[120:123]
	v_add3_u32 v0, s21, v160, v161
	v_add_u32_e32 v2, 0x8800, v0
	v_add_u32_e32 v0, 0x9000, v0
	ds_read_b64 v[124:125], v2
	ds_read_b64 v[126:127], v2 offset:32
	ds_read_b64 v[120:121], v2 offset:64
	ds_read_b64 v[122:123], v2 offset:96
	ds_read_b64 v[128:129], v0 offset:256
	ds_read_b64 v[130:131], v0 offset:288
	ds_read_b64 v[116:117], v0 offset:320
	ds_read_b64 v[118:119], v0 offset:352
	v_and_b32_e32 v2, 64, v213
	ds_read2_b32 v[174:175], v204 offset0:16 offset1:17
	ds_read2_b32 v[176:177], v204 offset0:18 offset1:19
	ds_read2_b32 v[178:179], v204 offset0:32 offset1:33
	ds_read2_b32 v[180:181], v204 offset0:34 offset1:35
	v_xor_b32_e32 v0, 16, v213
	v_add_u32_e32 v2, 64, v2
	v_cmp_lt_i32_e32 vcc, v0, v2
	s_mov_b32 s28, 0x3e0293ee
	s_waitcnt lgkmcnt(2)
	v_pk_fma_f32 v[168:169], v[172:173], s[28:29], v[176:177] op_sel_hi:[1,0,1]
	v_cndmask_b32_e32 v0, v213, v0, vcc
	v_lshlrev_b32_e32 v219, 2, v0
	v_xor_b32_e32 v0, 32, v213
	v_cmp_lt_i32_e32 vcc, v0, v2
	v_pk_fma_f32 v[2:3], v[170:171], s[28:29], v[174:175] op_sel_hi:[1,0,1]
	s_waitcnt lgkmcnt(0)
	v_pk_fma_f32 v[172:173], v[184:185], s[28:29], v[180:181] op_sel_hi:[1,0,1]
	v_pk_fma_f32 v[170:171], v[182:183], s[28:29], v[178:179] op_sel_hi:[1,0,1]
	ds_read2_b32 v[182:183], v204 offset0:48 offset1:49
	ds_read2_b32 v[184:185], v204 offset0:50 offset1:51
	ds_read2_b32 v[210:211], v204 offset0:64 offset1:65
	ds_read2_b32 v[216:217], v204 offset0:66 offset1:67
	v_cndmask_b32_e32 v0, v213, v0, vcc
	v_lshlrev_b32_e32 v220, 2, v0
	s_waitcnt lgkmcnt(3)
	v_pk_fma_f32 v[188:189], v[222:223], s[28:29], v[182:183] op_sel_hi:[1,0,1]
	s_waitcnt lgkmcnt(2)
	v_pk_fma_f32 v[152:153], v[224:225], s[28:29], v[184:185] op_sel_hi:[1,0,1]
	s_waitcnt lgkmcnt(0)
	v_pk_fma_f32 v[216:217], v[228:229], s[28:29], v[216:217] op_sel_hi:[1,0,1]
	v_cndmask_b32_e64 v222, v152, v214, s[4:5]
	v_cndmask_b32_e64 v216, v216, v214, s[4:5]
	v_pk_fma_f32 v[210:211], v[226:227], s[28:29], v[210:211] op_sel_hi:[1,0,1]
	v_cndmask_b32_e64 v215, v217, v214, s[4:5]
	v_cndmask_b32_e64 v221, v153, v214, s[4:5]
	v_cndmask_b32_e64 v218, v210, v214, s[4:5]
	v_cndmask_b32_e64 v224, v188, v214, s[4:5]
	v_cndmask_b32_e64 v217, v211, v214, s[4:5]
	v_cndmask_b32_e64 v223, v189, v214, s[4:5]
	v_max_f32_e32 v0, v222, v216
	v_max_f32_e32 v152, v221, v215
	v_max_f32_e32 v153, v224, v218
	v_max_f32_e32 v187, v223, v217
	v_max3_f32 v152, v169, v173, v152
	v_max3_f32 v0, v168, v172, v0
	v_max3_f32 v187, v3, v171, v187
	v_max3_f32 v153, v2, v170, v153
	v_max_f32_e32 v0, v0, v152
	v_max3_f32 v0, v153, v187, v0
	s_waitcnt lgkmcnt(0)
	v_mov_b32_e32 v152, v0
	s_nop 1
	v_permlane16_swap_b32_e32 v152, v0
	v_max_f32_e32 v0, v0, v152
	v_mov_b32_e32 v152, v0
	s_nop 1
	v_permlane32_swap_b32_e32 v152, v0
	v_max_f32_e32 v0, v0, v152
	v_sub_f32_e32 v152, v0, v186
	v_cmp_lt_f32_e32 vcc, 4.0, v152
	s_nop 1
	v_cndmask_b32_e32 v207, v186, v0, vcc
	v_sub_f32_e32 v0, v186, v207
	v_exp_f32_e32 v0, v0
	s_cbranch_vccz .LBB0_208
; __device__ __forceinline__ void attn_phase(unsigned char* lds, const Params& p, int jl, const bf16_t* proj, bf16_t* mix, int blk, int G, int tid) {
;     ...
;                 for (int qt = 0; qt < 2; ++qt) {
;                     const float* bp = BIAS + (575 - (qpos0 + qt * 16 - t * 64 - fq * 4));
; #pragma unroll
;                     for (int kt = 0; kt < 4; ++kt) { const f32x4 bv = {bp[kt * 16], bp[kt * 16 + 1], bp[kt * 16 + 2], bp[kt * 16 + 3]}; s[qt][kt] = s[qt][kt] * SC2 + bv; }
;                     if (nvk < 64) {
; #pragma unroll
;                         for (int kt = 0; kt < 4; ++kt)
; #pragma unroll
;                             for (int j = 0; j < 4; ++j) if (kt * 16 + fq * 4 + j >= nvk) s[qt][kt][j] = NEG_INF; }
;                     float mx;
;                     { const f32x4 m01 = __builtin_elementwise_max(s[qt][0], s[qt][1]), m23 = __builtin_elementwise_max(s[qt][2], s[qt][3]), m4 = __builtin_elementwise_max(m01, m23);
;                       mx = fmaxf(fmaxf(m4[0], m4[1]), fmaxf(m4[2], m4[3])); }
;                     mx = fmaxf(mx, __shfl_xor(mx, 16)); mx = fmaxf(mx, __shfl_xor(mx, 32));
;                     const float m_new = fmaxf(m_run[qt], mx), alpha = __builtin_amdgcn_exp2f(m_run[qt] - m_new);
; #pragma unroll
;                     for (int kt = 0; kt < 4; ++kt) { s[qt][kt] = s[qt][kt] - m_new;
; #pragma unroll
;                         for (int j = 0; j < 4; ++j) s[qt][kt][j] = __builtin_amdgcn_exp2f(s[qt][kt][j]); }
;                     const f32x4 sv4 = (s[qt][0] + s[qt][1]) + (s[qt][2] + s[qt][3]);
;                     const float ps = (sv4[0] + sv4[1]) + (sv4[2] + sv4[3]);
;                     l_run[qt] = l_run[qt] * alpha + ps; m_run[qt] = m_new;
;                     if (__any(alpha != 1.f)) {
; #pragma unroll
;                         for (int dt = 0; dt < 8; ++dt) o[qt][dt] = o[qt][dt] * alpha; }
	v_pk_mul_f32 v[106:107], v[106:107], v[0:1] op_sel_hi:[1,0]
	v_pk_mul_f32 v[104:105], v[104:105], v[0:1] op_sel_hi:[1,0]
	v_pk_mul_f32 v[98:99], v[98:99], v[0:1] op_sel_hi:[1,0]
	v_pk_mul_f32 v[96:97], v[96:97], v[0:1] op_sel_hi:[1,0]
	v_pk_mul_f32 v[90:91], v[90:91], v[0:1] op_sel_hi:[1,0]
	v_pk_mul_f32 v[88:89], v[88:89], v[0:1] op_sel_hi:[1,0]
	v_pk_mul_f32 v[86:87], v[86:87], v[0:1] op_sel_hi:[1,0]
	v_pk_mul_f32 v[84:85], v[84:85], v[0:1] op_sel_hi:[1,0]
	v_pk_mul_f32 v[50:51], v[50:51], v[0:1] op_sel_hi:[1,0]
	v_pk_mul_f32 v[48:49], v[48:49], v[0:1] op_sel_hi:[1,0]
	v_pk_mul_f32 v[46:47], v[46:47], v[0:1] op_sel_hi:[1,0]
	v_pk_mul_f32 v[44:45], v[44:45], v[0:1] op_sel_hi:[1,0]
	v_pk_mul_f32 v[42:43], v[42:43], v[0:1] op_sel_hi:[1,0]
	v_pk_mul_f32 v[40:41], v[40:41], v[0:1] op_sel_hi:[1,0]
	v_pk_mul_f32 v[38:39], v[38:39], v[0:1] op_sel_hi:[1,0]
	v_pk_mul_f32 v[36:37], v[36:37], v[0:1] op_sel_hi:[1,0]
.LBB0_208:
	ds_read2_b32 v[152:153], v204 offset0:2 offset1:3
	ds_read2_b32 v[186:187], v204 offset1:1
	v_pk_fma_f32 v[174:175], v[136:137], s[28:29], v[174:175] op_sel_hi:[1,0,1]
	v_pk_fma_f32 v[136:137], v[142:143], s[28:29], v[184:185] op_sel_hi:[1,0,1]
	v_pk_fma_f32 v[176:177], v[138:139], s[28:29], v[176:177] op_sel_hi:[1,0,1]
	v_cndmask_b32_e64 v143, v136, v214, s[4:5]
	s_waitcnt lgkmcnt(0)
	v_pk_fma_f32 v[186:187], v[132:133], s[28:29], v[186:187] op_sel_hi:[1,0,1]
	v_pk_fma_f32 v[132:133], v[146:147], s[28:29], v[180:181] op_sel_hi:[1,0,1]
	v_pk_fma_f32 v[188:189], v[134:135], s[28:29], v[152:153] op_sel_hi:[1,0,1]
	v_cndmask_b32_e64 v147, v132, v214, s[4:5]
	v_pk_fma_f32 v[134:135], v[144:145], s[28:29], v[178:179] op_sel_hi:[1,0,1]
	v_pk_fma_f32 v[138:139], v[140:141], s[28:29], v[182:183] op_sel_hi:[1,0,1]
	v_cndmask_b32_e64 v142, v137, v214, s[4:5]
	v_cndmask_b32_e64 v146, v133, v214, s[4:5]
	v_cndmask_b32_e64 v145, v138, v214, s[4:5]
	v_cndmask_b32_e64 v179, v134, v214, s[4:5]
	v_cndmask_b32_e64 v144, v139, v214, s[4:5]
	v_cndmask_b32_e64 v178, v135, v214, s[4:5]
	v_max_f32_e32 v132, v147, v143
	v_max_f32_e32 v133, v146, v142
	v_max_f32_e32 v134, v179, v145
	v_max_f32_e32 v135, v178, v144
	v_max3_f32 v133, v189, v177, v133
	v_max3_f32 v132, v188, v176, v132
	v_max3_f32 v135, v187, v175, v135
	v_max3_f32 v134, v186, v174, v134
	v_max_f32_e32 v132, v132, v133
	v_max3_f32 v132, v134, v135, v132
	s_waitcnt lgkmcnt(0)
	v_mov_b32_e32 v133, v132
	s_nop 1
	v_permlane16_swap_b32_e32 v133, v132
	v_max_f32_e32 v132, v132, v133
	v_mov_b32_e32 v133, v132
	s_nop 1
	v_permlane32_swap_b32_e32 v133, v132
	v_max_f32_e32 v132, v132, v133
	v_sub_f32_e32 v133, v132, v206
	v_cmp_lt_f32_e32 vcc, 4.0, v133
	s_nop 1
	v_cndmask_b32_e32 v141, v206, v132, vcc
	v_sub_f32_e32 v132, v206, v141
	v_exp_f32_e32 v140, v132
	s_cbranch_vccz .LBB0_210
	v_pk_mul_f32 v[34:35], v[34:35], v[140:141] op_sel_hi:[1,0]
	v_pk_mul_f32 v[32:33], v[32:33], v[140:141] op_sel_hi:[1,0]
	v_pk_mul_f32 v[30:31], v[30:31], v[140:141] op_sel_hi:[1,0]
	v_pk_mul_f32 v[28:29], v[28:29], v[140:141] op_sel_hi:[1,0]
	v_pk_mul_f32 v[26:27], v[26:27], v[140:141] op_sel_hi:[1,0]
	v_pk_mul_f32 v[24:25], v[24:25], v[140:141] op_sel_hi:[1,0]
	v_pk_mul_f32 v[22:23], v[22:23], v[140:141] op_sel_hi:[1,0]
	v_pk_mul_f32 v[20:21], v[20:21], v[140:141] op_sel_hi:[1,0]
	v_pk_mul_f32 v[18:19], v[18:19], v[140:141] op_sel_hi:[1,0]
	v_pk_mul_f32 v[16:17], v[16:17], v[140:141] op_sel_hi:[1,0]
	v_pk_mul_f32 v[14:15], v[14:15], v[140:141] op_sel_hi:[1,0]
	v_pk_mul_f32 v[12:13], v[12:13], v[140:141] op_sel_hi:[1,0]
	v_pk_mul_f32 v[10:11], v[10:11], v[140:141] op_sel_hi:[1,0]
	v_pk_mul_f32 v[8:9], v[8:9], v[140:141] op_sel_hi:[1,0]
	v_pk_mul_f32 v[6:7], v[6:7], v[140:141] op_sel_hi:[1,0]
	v_pk_mul_f32 v[4:5], v[4:5], v[140:141] op_sel_hi:[1,0]

; #define LAUNDER() int tid, blk = blk0, G = G0; asm volatile("v_mbcnt_lo_u32_b32 %0, -1, 0\n\tv_mbcnt_hi_u32_b32 %0, -1, %0" : "=v"(tid)); tid += wave_s * 64; asm volatile("" : "+v"(tid), "+s"(blk), "+s"(G))
; #define GRID_BAR() do { xcd_barrier(xbar); } while (0)
; __global__ void __launch_bounds__(512, 2) fwd_kernel(Params p) {
;     ...
;         else { LAUNDER(); attn_phase(lds, p, jl, proj, mix, blk, G, tid); }
;         GRID_BAR();
.LBB0_222:
	s_setprio 0
	s_mov_b64 s[2:3], 0
